# v6: + attention nomask softmax path for unmasked tiles + qkprep q/k loads hoisted to row start
# baseline (speedup 1.0000x reference)
; __device__ __forceinline__ void phase_qkprep(const Frame& F, int l, bool last, int ci, int nc) {
;     ...
;     for (int row = gw; row < TT; row += nw_) {
;         const bool lat = row < TL;
;         float cs[16], sn[16];
;         if (lat) { const int t = row & 4095, pos = (j < 4) ? (t >> 6) : (t & 63); const float* tp = F.ROPE + (pos * 32 + (j & 1) * 16) * 2;
; #pragma unroll
;             for (int q4 = 0; q4 < 8; ++q4) { const f32x4 v = *(const f32x4*)(tp + q4 * 4); cs[q4 * 2] = v[0]; sn[q4 * 2] = v[1]; cs[q4 * 2 + 1] = v[2]; sn[q4 * 2 + 1] = v[3]; } }
;         else {
; #pragma unroll
;             for (int e = 0; e < 16; ++e) { cs[e] = 1.f; sn[e] = 0.f; } }
;         f16* zp = F.Z + (size_t)row * ZLD;
; #pragma unroll
;         for (int pass = 0; pass < 2; ++pass) {
;             if (pass == 0 && !lat && last) continue;
;             if (pass == 1 && hd >= 2) continue;
;             f16* p = (pass == 0 ? zp + Z_AQ : zp + Z_AK) + hd * 128 + j * 16;
;             const f16x8 r0 = *(const f16x8*)p, r1 = *(const f16x8*)(p + 8);
.LBB0_581:
	global_load_dwordx4 v[112:115], v[66:67], off offset:16
	global_load_dwordx4 v[116:119], v[66:67], off
	v_add_co_u32_e32 v120, vcc, 0x1000, v66
	s_nop 1
	v_addc_co_u32_e32 v121, vcc, 0, v67, vcc
	global_load_dwordx4 v[104:107], v[120:121], off offset:16
	global_load_dwordx4 v[108:111], v[120:121], off
	s_cmpk_gt_i32 s0, 0x7fff
	s_cselect_b64 s[26:27], -1, 0
	s_and_b64 vcc, exec, s[26:27]
	s_cbranch_vccnz .LBB0_583
	s_lshr_b32 s3, s0, 6
	v_mov_b32_e32 v0, s0
	v_mov_b32_e32 v18, s3
	v_cndmask_b32_e64 v0, v0, v18, s[40:41]
	v_lshlrev_b32_e32 v0, 6, v0
	s_movk_i32 s3, 0xfc0
	v_and_or_b32 v0, v0, s3, v70
	v_lshlrev_b32_e32 v0, 2, v0
	global_load_dwordx4 v[18:21], v0, s[8:9] offset:112
	global_load_dwordx4 v[22:25], v0, s[8:9] offset:96
	global_load_dwordx4 v[26:29], v0, s[8:9] offset:80
	global_load_dwordx4 v[30:33], v0, s[8:9] offset:64
	global_load_dwordx4 v[34:37], v0, s[8:9] offset:48
	global_load_dwordx4 v[38:41], v0, s[8:9] offset:32
	global_load_dwordx4 v[42:45], v0, s[8:9] offset:16
	global_load_dwordx4 v[46:49], v0, s[8:9]
	s_waitcnt vmcnt(7)
	v_mov_b32_e32 v68, v19
	v_mov_b32_e32 v69, v21
	v_mov_b32_e32 v19, v20
	s_waitcnt vmcnt(6)
	v_mov_b32_e32 v20, v23
	v_mov_b32_e32 v21, v25
	v_mov_b32_e32 v23, v24
	s_waitcnt vmcnt(5)
	v_mov_b32_e32 v24, v27
	v_mov_b32_e32 v25, v29
	v_mov_b32_e32 v27, v28
	s_waitcnt vmcnt(4)
	v_mov_b32_e32 v28, v31
	v_mov_b32_e32 v29, v33
	v_mov_b32_e32 v31, v32
	s_waitcnt vmcnt(3)
	v_mov_b32_e32 v32, v35
	v_mov_b32_e32 v33, v37
	v_mov_b32_e32 v35, v36
	s_waitcnt vmcnt(2)
	v_mov_b32_e32 v36, v39
	v_mov_b32_e32 v37, v41
	v_mov_b32_e32 v39, v40
	s_waitcnt vmcnt(1)
	v_mov_b32_e32 v40, v43
	v_mov_b32_e32 v41, v45
	v_mov_b32_e32 v43, v44
	s_waitcnt vmcnt(0)
	v_mov_b32_e32 v44, v47
	v_mov_b32_e32 v45, v49
	v_mov_b32_e32 v47, v48
	s_and_b64 s[6:7], s[74:75], s[26:27]
	s_and_b64 vcc, exec, s[6:7]
	s_cbranch_vccz .LBB0_584
	s_branch .LBB0_585

; __device__ __forceinline__ void phase_qkprep(const Frame& F, int l, bool last, int ci, int nc) {
;     ...
;             if (pass == 0 && !lat && last) continue;
;             if (pass == 1 && hd >= 2) continue;
;             f16* p = (pass == 0 ? zp + Z_AQ : zp + Z_AK) + hd * 128 + j * 16;
;             const f16x8 r0 = *(const f16x8*)p, r1 = *(const f16x8*)(p + 8);
;             float x[16]; float ss = 0.f;
; #pragma unroll
;             for (int e = 0; e < 8; ++e) { x[e] = (float)r0[e]; x[8 + e] = (float)r1[e]; }
; #pragma unroll
;             for (int e = 0; e < 16; ++e) ss += x[e] * x[e];
;             ss += __shfl_xor(ss, 1); ss += __shfl_xor(ss, 2); ss += __shfl_xor(ss, 4);
;             const float rstd = rsqrtf(ss * (1.0f / 128.0f) + 1e-6f);
;             float o[16];
; #pragma unroll
;             for (int e = 0; e < 16; ++e) { const float xn = x[e] * rstd * (pass == 0 ? wq[e] : wk[e]); const float pn = __shfl_xor(xn, 2);
;                 o[e] = second ? (pn * sn[e] + xn * cs[e]) : (xn * cs[e] - pn * sn[e]); }
;             u32x4 w0, w1; w0.x = pk_f16(o[0], o[1]); w0.y = pk_f16(o[2], o[3]); w0.z = pk_f16(o[4], o[5]); w0.w = pk_f16(o[6], o[7]);
;             w1.x = pk_f16(o[8], o[9]); w1.y = pk_f16(o[10], o[11]); w1.z = pk_f16(o[12], o[13]); w1.w = pk_f16(o[14], o[15]);
;             *(u32x4*)p = w0; *(u32x4*)(p + 8) = w1;
.LBB0_584:
	v_add_co_u32_e32 v48, vcc, 0x1000, v66
	v_and_b32_e32 v71, 64, v237
	s_nop 0
	v_addc_co_u32_e32 v49, vcc, 0, v67, vcc
	v_xor_b32_e32 v0, 1, v237
	v_add_u32_e32 v71, 64, v71
	v_cmp_lt_i32_e32 vcc, v0, v71
	s_waitcnt vmcnt(0)
	v_cvt_f32_f16_e32 v80, v107
	v_cvt_f32_f16_e32 v88, v108
	v_cvt_f32_f16_sdwa v89, v108 dst_sel:DWORD dst_unused:UNUSED_PAD src0_sel:WORD_1
	v_cvt_f32_f16_sdwa v81, v107 dst_sel:DWORD dst_unused:UNUSED_PAD src0_sel:WORD_1
	v_cvt_f32_f16_e32 v82, v106
	v_cvt_f32_f16_sdwa v83, v106 dst_sel:DWORD dst_unused:UNUSED_PAD src0_sel:WORD_1
	v_cvt_f32_f16_e32 v74, v105
	v_cvt_f32_f16_sdwa v75, v105 dst_sel:DWORD dst_unused:UNUSED_PAD src0_sel:WORD_1
	v_cvt_f32_f16_e32 v84, v104
	v_cvt_f32_f16_sdwa v85, v104 dst_sel:DWORD dst_unused:UNUSED_PAD src0_sel:WORD_1
	v_cvt_f32_f16_e32 v72, v111
	v_cvt_f32_f16_sdwa v73, v111 dst_sel:DWORD dst_unused:UNUSED_PAD src0_sel:WORD_1
	v_cvt_f32_f16_e32 v86, v110
	v_cvt_f32_f16_sdwa v87, v110 dst_sel:DWORD dst_unused:UNUSED_PAD src0_sel:WORD_1
	v_cvt_f32_f16_e32 v78, v109
	v_cvt_f32_f16_sdwa v79, v109 dst_sel:DWORD dst_unused:UNUSED_PAD src0_sel:WORD_1
	v_pk_mul_f32 v[102:103], v[88:89], v[88:89]
	v_pk_mul_f32 v[98:99], v[86:87], v[86:87]
	v_add_f32_e32 v102, v102, v103
	v_pk_mul_f32 v[100:101], v[78:79], v[78:79]
	v_pk_mul_f32 v[96:97], v[72:73], v[72:73]
	v_add_f32_e32 v100, v100, v102
	v_add_f32_e32 v100, v101, v100
	v_add_f32_e32 v98, v98, v100
	v_add_f32_e32 v98, v99, v98
	v_add_f32_e32 v96, v96, v98
	v_pk_mul_f32 v[94:95], v[84:85], v[84:85]
	v_add_f32_e32 v96, v97, v96
	v_add_f32_e32 v94, v94, v96
	v_pk_mul_f32 v[92:93], v[74:75], v[74:75]
	v_add_f32_e32 v94, v95, v94
	v_add_f32_e32 v92, v92, v94
	v_pk_mul_f32 v[90:91], v[82:83], v[82:83]
	v_add_f32_e32 v92, v93, v92
	v_add_f32_e32 v90, v90, v92
	v_pk_mul_f32 v[76:77], v[80:81], v[80:81]
	v_add_f32_e32 v90, v91, v90
	v_cndmask_b32_e32 v0, v237, v0, vcc
	v_add_f32_e32 v76, v76, v90
	v_lshlrev_b32_e32 v0, 2, v0
	v_add_f32_e32 v76, v77, v76
	ds_bpermute_b32 v0, v0, v76
	v_xor_b32_e32 v77, 2, v237
	v_cmp_lt_i32_e32 vcc, v77, v71
	s_waitcnt lgkmcnt(0)
	v_add_f32_e32 v0, v76, v0
	v_cndmask_b32_e32 v77, v237, v77, vcc
	v_lshlrev_b32_e32 v103, 2, v77
	ds_bpermute_b32 v76, v103, v0
	v_xor_b32_e32 v77, 4, v237
	v_cmp_lt_i32_e32 vcc, v77, v71
	s_waitcnt lgkmcnt(0)
	v_add_f32_e32 v0, v0, v76
	v_cndmask_b32_e32 v71, v237, v77, vcc
	v_lshlrev_b32_e32 v71, 2, v71
	ds_bpermute_b32 v71, v71, v0
	s_waitcnt lgkmcnt(0)
	v_add_f32_e32 v0, v0, v71
	v_fmamk_f32 v0, v0, 0x3c000000, v235
	v_mul_f32_e32 v71, 0x4b800000, v0
	v_cmp_gt_f32_e32 vcc, s88, v0
	s_nop 1
	v_cndmask_b32_e32 v0, v0, v71, vcc
	v_rsq_f32_e32 v0, v0
	s_nop 0
	v_mul_f32_e32 v71, 0x45800000, v0
	v_cndmask_b32_e32 v0, v0, v71, vcc
	v_pk_mul_f32 v[76:77], v[0:1], v[88:89] op_sel_hi:[0,1]
	v_pk_mul_f32 v[78:79], v[0:1], v[78:79] op_sel_hi:[0,1]
	v_pk_mul_f32 v[86:87], v[0:1], v[86:87] op_sel_hi:[0,1]
	v_pk_mul_f32 v[72:73], v[0:1], v[72:73] op_sel_hi:[0,1]
	v_pk_mul_f32 v[84:85], v[0:1], v[84:85] op_sel_hi:[0,1]
	v_pk_mul_f32 v[74:75], v[0:1], v[74:75] op_sel_hi:[0,1]
	v_pk_mul_f32 v[82:83], v[0:1], v[82:83] op_sel_hi:[0,1]
	v_pk_mul_f32 v[80:81], v[0:1], v[80:81] op_sel_hi:[0,1]
	v_pk_mul_f32 v[76:77], v[50:51], v[76:77]
	v_pk_mul_f32 v[78:79], v[52:53], v[78:79]
	v_pk_mul_f32 v[86:87], v[54:55], v[86:87]
	v_pk_mul_f32 v[72:73], v[56:57], v[72:73]
	v_pk_mul_f32 v[84:85], v[58:59], v[84:85]
	v_pk_mul_f32 v[74:75], v[60:61], v[74:75]
	v_pk_mul_f32 v[82:83], v[62:63], v[82:83]
	v_pk_mul_f32 v[80:81], v[64:65], v[80:81]
	ds_bpermute_b32 v88, v103, v76
	ds_bpermute_b32 v89, v103, v77
	ds_bpermute_b32 v90, v103, v78
	ds_bpermute_b32 v91, v103, v79
	ds_bpermute_b32 v92, v103, v86
	ds_bpermute_b32 v93, v103, v87
	ds_bpermute_b32 v94, v103, v72
	ds_bpermute_b32 v95, v103, v73
	ds_bpermute_b32 v96, v103, v84
	ds_bpermute_b32 v97, v103, v85
	ds_bpermute_b32 v98, v103, v74
	ds_bpermute_b32 v99, v103, v75
	ds_bpermute_b32 v100, v103, v82
	ds_bpermute_b32 v101, v103, v83
	ds_bpermute_b32 v102, v103, v80
	ds_bpermute_b32 v103, v103, v81
	s_waitcnt lgkmcnt(14)
	v_pk_mul_f32 v[88:89], v[44:45], v[88:89]
	s_waitcnt lgkmcnt(12)
	v_pk_mul_f32 v[90:91], v[40:41], v[90:91]
	s_waitcnt lgkmcnt(10)
	v_pk_mul_f32 v[92:93], v[36:37], v[92:93]
	s_waitcnt lgkmcnt(8)
	v_pk_mul_f32 v[94:95], v[32:33], v[94:95]
	s_waitcnt lgkmcnt(6)
	v_pk_mul_f32 v[96:97], v[28:29], v[96:97]
	s_waitcnt lgkmcnt(4)
	v_pk_mul_f32 v[98:99], v[24:25], v[98:99]
	s_waitcnt lgkmcnt(2)
	v_pk_mul_f32 v[100:101], v[20:21], v[100:101]
	s_waitcnt lgkmcnt(0)
	v_pk_mul_f32 v[102:103], v[68:69], v[102:103]
	v_cndmask_b32_e64 v89, v89, -v89, s[38:39]
	v_cndmask_b32_e64 v88, v88, -v88, s[38:39]
	v_cndmask_b32_e64 v91, v91, -v91, s[38:39]
	v_cndmask_b32_e64 v90, v90, -v90, s[38:39]
	v_cndmask_b32_e64 v93, v93, -v93, s[38:39]
	v_cndmask_b32_e64 v92, v92, -v92, s[38:39]
	v_cndmask_b32_e64 v95, v95, -v95, s[38:39]
	v_cndmask_b32_e64 v94, v94, -v94, s[38:39]
	v_cndmask_b32_e64 v97, v97, -v97, s[38:39]
	v_cndmask_b32_e64 v96, v96, -v96, s[38:39]
	v_cndmask_b32_e64 v99, v99, -v99, s[38:39]
	v_cndmask_b32_e64 v98, v98, -v98, s[38:39]
	v_cndmask_b32_e64 v101, v101, -v101, s[38:39]
	v_cndmask_b32_e64 v100, v100, -v100, s[38:39]
	v_cndmask_b32_e64 v103, v103, -v103, s[38:39]
	v_cndmask_b32_e64 v102, v102, -v102, s[38:39]
	v_pk_fma_f32 v[76:77], v[46:47], v[76:77], v[88:89]
	v_pk_fma_f32 v[78:79], v[42:43], v[78:79], v[90:91]
	v_pk_fma_f32 v[86:87], v[38:39], v[86:87], v[92:93]
	v_pk_fma_f32 v[88:89], v[34:35], v[72:73], v[94:95]
	v_pk_fma_f32 v[84:85], v[30:31], v[84:85], v[96:97]
	v_pk_fma_f32 v[90:91], v[26:27], v[74:75], v[98:99]
	v_pk_fma_f32 v[82:83], v[22:23], v[82:83], v[100:101]
	v_pk_fma_f32 v[80:81], v[18:19], v[80:81], v[102:103]
	v_cvt_pk_f16_f32 v72, v76, v77
	v_cvt_pk_f16_f32 v73, v78, v79
	v_cvt_pk_f16_f32 v74, v86, v87
	v_cvt_pk_f16_f32 v75, v88, v89
	v_cvt_pk_f16_f32 v76, v84, v85
	v_cvt_pk_f16_f32 v77, v90, v91
	v_cvt_pk_f16_f32 v78, v82, v83
	v_cvt_pk_f16_f32 v79, v80, v81
	global_store_dwordx4 v[48:49], v[72:75], off
	global_store_dwordx4 v[48:49], v[76:79], off offset:16
; __device__ __forceinline__ void phase_qkprep(const Frame& F, int l, bool last, int ci, int nc) {
;     ...
;             if (pass == 1 && hd >= 2) continue;
;             f16* p = (pass == 0 ? zp + Z_AQ : zp + Z_AK) + hd * 128 + j * 16;
;             const f16x8 r0 = *(const f16x8*)p, r1 = *(const f16x8*)(p + 8);
;             float x[16]; float ss = 0.f;
; #pragma unroll
;             for (int e = 0; e < 8; ++e) { x[e] = (float)r0[e]; x[8 + e] = (float)r1[e]; }
; #pragma unroll
;             for (int e = 0; e < 16; ++e) ss += x[e] * x[e];
;             ss += __shfl_xor(ss, 1); ss += __shfl_xor(ss, 2); ss += __shfl_xor(ss, 4);
;             const float rstd = rsqrtf(ss * (1.0f / 128.0f) + 1e-6f);
;             float o[16];
; #pragma unroll
;             for (int e = 0; e < 16; ++e) { const float xn = x[e] * rstd * (pass == 0 ? wq[e] : wk[e]); const float pn = __shfl_xor(xn, 2);
;                 o[e] = second ? (pn * sn[e] + xn * cs[e]) : (xn * cs[e] - pn * sn[e]); }
;             u32x4 w0, w1; w0.x = pk_f16(o[0], o[1]); w0.y = pk_f16(o[2], o[3]); w0.z = pk_f16(o[4], o[5]); w0.w = pk_f16(o[6], o[7]);
;             w1.x = pk_f16(o[8], o[9]); w1.y = pk_f16(o[10], o[11]); w1.z = pk_f16(o[12], o[13]); w1.w = pk_f16(o[14], o[15]);
;             *(u32x4*)p = w0; *(u32x4*)(p + 8) = w1;
.LBB0_585:
	s_and_saveexec_b64 s[26:27], s[42:43]
	s_cbranch_execz .LBB0_580
	v_and_b32_e32 v48, 64, v237
	v_add_u32_e32 v71, 64, v48
	v_xor_b32_e32 v0, 1, v237
	v_cmp_lt_i32_e32 vcc, v0, v71
	s_waitcnt vmcnt(2)
	v_cvt_f32_f16_sdwa v81, v113 dst_sel:DWORD dst_unused:UNUSED_PAD src0_sel:WORD_1
	v_cvt_f32_f16_sdwa v85, v117 dst_sel:DWORD dst_unused:UNUSED_PAD src0_sel:WORD_1
	v_cvt_f32_f16_e32 v84, v117
	v_cvt_f32_f16_sdwa v77, v116 dst_sel:DWORD dst_unused:UNUSED_PAD src0_sel:WORD_1
	v_cvt_f32_f16_e32 v76, v116
	v_cvt_f32_f16_sdwa v83, v119 dst_sel:DWORD dst_unused:UNUSED_PAD src0_sel:WORD_1
	v_cvt_f32_f16_e32 v82, v119
	v_cvt_f32_f16_sdwa v79, v118 dst_sel:DWORD dst_unused:UNUSED_PAD src0_sel:WORD_1
	v_cvt_f32_f16_e32 v78, v118
	v_pk_mul_f32 v[100:101], v[76:77], v[76:77]
	v_pk_mul_f32 v[98:99], v[84:85], v[84:85]
	v_add_f32_e32 v100, v100, v101
	v_add_f32_e32 v98, v98, v100
	v_cvt_f32_f16_e32 v80, v113
	v_cvt_f32_f16_sdwa v73, v112 dst_sel:DWORD dst_unused:UNUSED_PAD src0_sel:WORD_1
	v_cvt_f32_f16_e32 v72, v112
	v_pk_mul_f32 v[96:97], v[78:79], v[78:79]
	v_add_f32_e32 v98, v99, v98
	v_add_f32_e32 v96, v96, v98
	v_pk_mul_f32 v[94:95], v[82:83], v[82:83]
	v_add_f32_e32 v96, v97, v96
	v_add_f32_e32 v94, v94, v96
	v_cvt_f32_f16_sdwa v49, v115 dst_sel:DWORD dst_unused:UNUSED_PAD src0_sel:WORD_1
	v_cvt_f32_f16_e32 v48, v115
	v_cvt_f32_f16_sdwa v75, v114 dst_sel:DWORD dst_unused:UNUSED_PAD src0_sel:WORD_1
	v_cvt_f32_f16_e32 v74, v114
	v_pk_mul_f32 v[92:93], v[72:73], v[72:73]
	v_add_f32_e32 v94, v95, v94
	v_add_f32_e32 v92, v92, v94
	v_pk_mul_f32 v[90:91], v[80:81], v[80:81]
	v_add_f32_e32 v92, v93, v92
	v_add_f32_e32 v90, v90, v92
	v_pk_mul_f32 v[88:89], v[74:75], v[74:75]
	v_add_f32_e32 v90, v91, v90
	v_add_f32_e32 v88, v88, v90
	v_pk_mul_f32 v[86:87], v[48:49], v[48:49]
	v_add_f32_e32 v88, v89, v88
	v_cndmask_b32_e32 v0, v237, v0, vcc
	v_add_f32_e32 v86, v86, v88
	v_lshlrev_b32_e32 v0, 2, v0
	v_add_f32_e32 v86, v87, v86
	ds_bpermute_b32 v0, v0, v86
	v_xor_b32_e32 v87, 2, v237
	v_cmp_lt_i32_e32 vcc, v87, v71
	s_waitcnt lgkmcnt(0)
	v_add_f32_e32 v0, v86, v0
	v_cndmask_b32_e32 v87, v237, v87, vcc
	v_lshlrev_b32_e32 v101, 2, v87
	ds_bpermute_b32 v86, v101, v0
	v_xor_b32_e32 v87, 4, v237
	v_cmp_lt_i32_e32 vcc, v87, v71
	s_waitcnt lgkmcnt(0)
	v_add_f32_e32 v0, v0, v86
	v_cndmask_b32_e32 v71, v237, v87, vcc
	v_lshlrev_b32_e32 v71, 2, v71
	ds_bpermute_b32 v71, v71, v0
	s_waitcnt lgkmcnt(0)
	v_add_f32_e32 v0, v0, v71
	v_fmamk_f32 v0, v0, 0x3c000000, v235
	v_mul_f32_e32 v71, 0x4b800000, v0
	v_cmp_gt_f32_e32 vcc, s88, v0
	s_nop 1
	v_cndmask_b32_e32 v0, v0, v71, vcc
	v_rsq_f32_e32 v0, v0
	s_nop 0
	v_mul_f32_e32 v71, 0x45800000, v0
	v_cndmask_b32_e32 v0, v0, v71, vcc
	v_pk_mul_f32 v[76:77], v[0:1], v[76:77] op_sel_hi:[0,1]
	v_pk_mul_f32 v[84:85], v[0:1], v[84:85] op_sel_hi:[0,1]
	v_pk_mul_f32 v[78:79], v[0:1], v[78:79] op_sel_hi:[0,1]
	v_pk_mul_f32 v[82:83], v[0:1], v[82:83] op_sel_hi:[0,1]
	v_pk_mul_f32 v[72:73], v[0:1], v[72:73] op_sel_hi:[0,1]
	v_pk_mul_f32 v[80:81], v[0:1], v[80:81] op_sel_hi:[0,1]
	v_pk_mul_f32 v[74:75], v[0:1], v[74:75] op_sel_hi:[0,1]
	v_pk_mul_f32 v[48:49], v[0:1], v[48:49] op_sel_hi:[0,1]
	v_pk_mul_f32 v[76:77], v[14:15], v[76:77]
	v_pk_mul_f32 v[84:85], v[16:17], v[84:85]
	v_pk_mul_f32 v[78:79], v[10:11], v[78:79]
	v_pk_mul_f32 v[82:83], v[12:13], v[82:83]
	v_pk_mul_f32 v[72:73], v[6:7], v[72:73]
	v_pk_mul_f32 v[80:81], v[8:9], v[80:81]
	v_pk_mul_f32 v[74:75], v[2:3], v[74:75]
	v_pk_mul_f32 v[48:49], v[4:5], v[48:49]
	ds_bpermute_b32 v86, v101, v76
	ds_bpermute_b32 v87, v101, v77
	ds_bpermute_b32 v88, v101, v84
	ds_bpermute_b32 v89, v101, v85
	ds_bpermute_b32 v90, v101, v78
	ds_bpermute_b32 v91, v101, v79
	ds_bpermute_b32 v92, v101, v82
	ds_bpermute_b32 v93, v101, v83
	ds_bpermute_b32 v94, v101, v72
	ds_bpermute_b32 v95, v101, v73
	ds_bpermute_b32 v96, v101, v80
	ds_bpermute_b32 v97, v101, v81
	ds_bpermute_b32 v98, v101, v74
	ds_bpermute_b32 v99, v101, v75
	ds_bpermute_b32 v100, v101, v48
	ds_bpermute_b32 v101, v101, v49
	s_waitcnt lgkmcnt(14)
	v_pk_mul_f32 v[44:45], v[44:45], v[86:87]
	s_waitcnt lgkmcnt(12)
	v_pk_mul_f32 v[40:41], v[40:41], v[88:89]
	s_waitcnt lgkmcnt(10)
	v_pk_mul_f32 v[36:37], v[36:37], v[90:91]
	s_waitcnt lgkmcnt(8)
	v_pk_mul_f32 v[32:33], v[32:33], v[92:93]
	s_waitcnt lgkmcnt(6)
	v_pk_mul_f32 v[28:29], v[28:29], v[94:95]
	s_waitcnt lgkmcnt(4)
	v_pk_mul_f32 v[24:25], v[24:25], v[96:97]
	s_waitcnt lgkmcnt(2)
	v_pk_mul_f32 v[20:21], v[20:21], v[98:99]
	s_waitcnt lgkmcnt(0)
	v_pk_mul_f32 v[68:69], v[68:69], v[100:101]
	v_cndmask_b32_e64 v45, v45, -v45, s[38:39]
	v_cndmask_b32_e64 v44, v44, -v44, s[38:39]
	v_cndmask_b32_e64 v41, v41, -v41, s[38:39]
	v_cndmask_b32_e64 v40, v40, -v40, s[38:39]
	v_cndmask_b32_e64 v37, v37, -v37, s[38:39]
	v_cndmask_b32_e64 v36, v36, -v36, s[38:39]
	v_cndmask_b32_e64 v33, v33, -v33, s[38:39]
	v_cndmask_b32_e64 v32, v32, -v32, s[38:39]
	v_cndmask_b32_e64 v29, v29, -v29, s[38:39]
	v_cndmask_b32_e64 v28, v28, -v28, s[38:39]
	v_cndmask_b32_e64 v25, v25, -v25, s[38:39]
	v_cndmask_b32_e64 v24, v24, -v24, s[38:39]
	v_cndmask_b32_e64 v21, v21, -v21, s[38:39]
	v_cndmask_b32_e64 v20, v20, -v20, s[38:39]
	v_cndmask_b32_e64 v69, v69, -v69, s[38:39]
	v_cndmask_b32_e64 v68, v68, -v68, s[38:39]
	v_pk_fma_f32 v[44:45], v[46:47], v[76:77], v[44:45]
	v_pk_fma_f32 v[40:41], v[42:43], v[84:85], v[40:41]
	v_pk_fma_f32 v[36:37], v[38:39], v[78:79], v[36:37]
	v_pk_fma_f32 v[32:33], v[34:35], v[82:83], v[32:33]
	v_pk_fma_f32 v[28:29], v[30:31], v[72:73], v[28:29]
	v_pk_fma_f32 v[24:25], v[26:27], v[80:81], v[24:25]
	v_pk_fma_f32 v[26:27], v[22:23], v[74:75], v[20:21]
	v_pk_fma_f32 v[30:31], v[18:19], v[48:49], v[68:69]
	v_cvt_pk_f16_f32 v18, v44, v45
	v_cvt_pk_f16_f32 v19, v40, v41
	v_cvt_pk_f16_f32 v20, v36, v37
	v_cvt_pk_f16_f32 v21, v32, v33
	v_cvt_pk_f16_f32 v22, v28, v29
	v_cvt_pk_f16_f32 v23, v24, v25
	v_cvt_pk_f16_f32 v24, v26, v27
	v_cvt_pk_f16_f32 v25, v30, v31
	global_store_dwordx4 v[66:67], v[18:21], off
	global_store_dwordx4 v[66:67], v[22:25], off offset:16
	s_branch .LBB0_580

; #define LAS __attribute__((address_space(3)))
; __device__ __forceinline__ void phase_attn(const Frame& F, int l, bool last, int ai, int na) {
;     ...
;             const int kpos0 = wlo + t * 64, q0w = qb * 128 + (w & 3) * 32;
;             const bool win = (t < nwin) && !(kpos0 <= q0w + 65 && kpos0 >= q0w - 97);
;             if ((t < nwin) && (kpos0 > q0w + 159 || kpos0 < q0w - 191)) continue;
;             f32x16 sacc[2];
; #pragma unroll
;             for (int kt = 0; kt < 2; ++kt) {
; #pragma unroll
;                 for (int e = 0; e < 16; ++e) sacc[kt][e] = 0.f;
; #pragma unroll
;                 for (int s = 0; s < 8; ++s) { const f16x8 a = *(const LAS f16x8*)(lds + bo + AT_K + ((kt * 32 + r32) * 136 + s * 16 + hh * 8) * 2);
;                     sacc[kt] = __builtin_amdgcn_mfma_f32_32x32x16_f16(a, qf[s], sacc[kt], 0, 0, 0); } }
;             float mx = -1e30f;
; #pragma unroll
;             for (int kt = 0; kt < 2; ++kt)
; #pragma unroll
;                 for (int e = 0; e < 16; ++e) {
;                     if (win) { const int kp = kpos0 + kt * 32 + (e & 3) + 8 * (e >> 2) + 4 * hh; const int dd = kp - qpos; if (dd > 128 || dd < -128) sacc[kt][e] = -1e30f; }
;                     mx = fmaxf(mx, sacc[kt][e]); }
;             mx = fmaxf(mx, __shfl_xor(mx, 32));
.LBB0_614:
	s_andn2_b64 vcc, exec, s[10:11]
	s_cbranch_vccnz .LBB0_618
	s_cmp_gt_i32 s41, s34
	s_cselect_b64 s[10:11], -1, 0
	s_cmp_lt_i32 s41, s35
	s_cselect_b64 s[42:43], -1, 0
	s_or_b64 s[10:11], s[10:11], s[42:43]
	s_and_b64 s[10:11], s[2:3], s[10:11]
	s_add_i32 s2, s40, 0
	v_add_u32_e32 v14, s2, v189
	v_add_u32_e32 v15, s2, v190
	s_mov_b32 s3, 0xf149f2ca
	ds_read_b128 v[2:5], v14
	ds_read_b128 v[6:9], v15
	ds_read_b128 v[10:13], v14 offset:32
	ds_read_b128 v[200:203], v15 offset:32
	ds_read_b128 v[242:245], v14 offset:64
	ds_read_b128 v[246:249], v15 offset:64
	s_waitcnt lgkmcnt(5)
	v_mfma_f32_32x32x16_f16 v[96:111], v[2:5], v[112:115], 0
	ds_read_b128 v[2:5], v14 offset:96
	s_waitcnt lgkmcnt(5)
	v_mfma_f32_32x32x16_f16 v[80:95], v[6:9], v[112:115], 0
	ds_read_b128 v[6:9], v15 offset:96
	s_waitcnt lgkmcnt(5)
	v_mfma_f32_32x32x16_f16 v[96:111], v[10:13], v[116:119], v[96:111]
	ds_read_b128 v[10:13], v14 offset:128
	s_waitcnt lgkmcnt(5)
	v_mfma_f32_32x32x16_f16 v[80:95], v[200:203], v[116:119], v[80:95]
	ds_read_b128 v[200:203], v15 offset:128
	s_waitcnt lgkmcnt(5)
	v_mfma_f32_32x32x16_f16 v[96:111], v[242:245], v[120:123], v[96:111]
	ds_read_b128 v[242:245], v14 offset:160
	s_waitcnt lgkmcnt(5)
	v_mfma_f32_32x32x16_f16 v[80:95], v[246:249], v[120:123], v[80:95]
	ds_read_b128 v[246:249], v15 offset:160
	s_waitcnt lgkmcnt(5)
	v_mfma_f32_32x32x16_f16 v[96:111], v[2:5], v[124:127], v[96:111]
	ds_read_b128 v[2:5], v14 offset:192
	s_waitcnt lgkmcnt(5)
	v_mfma_f32_32x32x16_f16 v[80:95], v[6:9], v[124:127], v[80:95]
	ds_read_b128 v[6:9], v15 offset:192
	s_waitcnt lgkmcnt(5)
	v_mfma_f32_32x32x16_f16 v[96:111], v[10:13], v[128:131], v[96:111]
	ds_read_b128 v[10:13], v14 offset:224
	s_waitcnt lgkmcnt(5)
	v_mfma_f32_32x32x16_f16 v[80:95], v[200:203], v[128:131], v[80:95]
	ds_read_b128 v[200:203], v15 offset:224
	s_waitcnt lgkmcnt(5)
	v_mfma_f32_32x32x16_f16 v[96:111], v[242:245], v[132:135], v[96:111]
	s_waitcnt lgkmcnt(4)
	v_mfma_f32_32x32x16_f16 v[80:95], v[246:249], v[132:135], v[80:95]
	s_waitcnt lgkmcnt(3)
	v_mfma_f32_32x32x16_f16 v[96:111], v[2:5], v[136:139], v[96:111]
	s_waitcnt lgkmcnt(2)
	v_mfma_f32_32x32x16_f16 v[80:95], v[6:9], v[136:139], v[80:95]
	s_waitcnt lgkmcnt(1)
	v_mfma_f32_32x32x16_f16 v[96:111], v[10:13], v[140:143], v[96:111]
	s_waitcnt lgkmcnt(0)
	v_mfma_f32_32x32x16_f16 v[80:95], v[200:203], v[140:143], v[80:95]
	s_cmp_eq_u64 s[10:11], 0
	s_cbranch_scc1 .Lattn_nomask
	v_add_u32_e32 v0, s38, v229
	v_add_u32_e32 v6, 0xffffff82, v0
	v_add_u32_e32 v7, 0xffffff87, v0
	v_add_u32_e32 v8, 0xffffff88, v0
	v_add_u32_e32 v9, 0xffffff89, v0
	v_add_u32_e32 v10, 0xffffff8a, v0
	s_nop 3
	v_add_u32_e32 v2, 0xffffff7f, v0
	v_cmp_gt_u32_e32 vcc, s83, v2
	s_and_b64 vcc, s[10:11], vcc
	v_add_u32_e32 v3, 0xffffff80, v0
	v_cndmask_b32_e32 v2, v96, v241, vcc
	v_cmp_gt_u32_e32 vcc, s83, v3
	s_and_b64 vcc, s[10:11], vcc
	v_add_u32_e32 v5, 0xffffff81, v0
	v_cndmask_b32_e32 v3, v97, v241, vcc
	v_cmp_gt_u32_e32 vcc, s83, v5
	s_and_b64 vcc, s[10:11], vcc
	v_add_u32_e32 v11, 0xffffff8f, v0
	v_cndmask_b32_e32 v5, v98, v241, vcc
	v_cmp_gt_u32_e32 vcc, s83, v6
	s_and_b64 vcc, s[10:11], vcc
	v_add_u32_e32 v12, 0xffffff90, v0
	v_cndmask_b32_e32 v6, v99, v241, vcc
	v_cmp_gt_u32_e32 vcc, s83, v7
	s_and_b64 vcc, s[10:11], vcc
	v_add_u32_e32 v13, 0xffffff91, v0
	v_cndmask_b32_e32 v7, v100, v241, vcc
	v_cmp_gt_u32_e32 vcc, s83, v8
	s_and_b64 vcc, s[10:11], vcc
	v_add_u32_e32 v14, 0xffffff92, v0
	v_cndmask_b32_e32 v8, v101, v241, vcc
	v_cmp_gt_u32_e32 vcc, s83, v9
	s_and_b64 vcc, s[10:11], vcc
	v_add_u32_e32 v15, 0xffffff97, v0
	v_cndmask_b32_e32 v9, v102, v241, vcc
	v_cmp_gt_u32_e32 vcc, s83, v10
	s_and_b64 vcc, s[10:11], vcc
	v_add_u32_e32 v96, 0xffffff98, v0
	v_cndmask_b32_e32 v10, v103, v241, vcc
	v_cmp_gt_u32_e32 vcc, s83, v11
	s_and_b64 vcc, s[10:11], vcc
	v_add_u32_e32 v97, 0xffffff99, v0
	v_cndmask_b32_e32 v11, v104, v241, vcc
	v_cmp_gt_u32_e32 vcc, s83, v12
	s_and_b64 vcc, s[10:11], vcc
	v_add_u32_e32 v98, 0xffffff9a, v0
	v_cndmask_b32_e32 v12, v105, v241, vcc
	v_cmp_gt_u32_e32 vcc, s83, v13
	s_and_b64 vcc, s[10:11], vcc
	v_add_u32_e32 v99, 0xffffff9f, v0
	v_cndmask_b32_e32 v13, v106, v241, vcc
	v_cmp_gt_u32_e32 vcc, s83, v14
	s_and_b64 vcc, s[10:11], vcc
	v_max3_f32 v4, v2, s3, v3
	v_cndmask_b32_e32 v14, v107, v241, vcc
	v_cmp_gt_u32_e32 vcc, s83, v15
	s_and_b64 vcc, s[10:11], vcc
	v_max3_f32 v4, v4, v5, v6
	v_cndmask_b32_e32 v15, v108, v241, vcc
	v_cmp_gt_u32_e32 vcc, s83, v96
	s_and_b64 vcc, s[10:11], vcc
	v_max3_f32 v4, v4, v7, v8
	v_cndmask_b32_e32 v96, v109, v241, vcc
	v_cmp_gt_u32_e32 vcc, s83, v97
	s_and_b64 vcc, s[10:11], vcc
	v_max3_f32 v4, v4, v9, v10
	v_cndmask_b32_e32 v97, v110, v241, vcc
	v_cmp_gt_u32_e32 vcc, s83, v98
	s_and_b64 vcc, s[10:11], vcc
	v_max3_f32 v4, v4, v11, v12
	v_cndmask_b32_e32 v98, v111, v241, vcc
	v_cmp_gt_u32_e32 vcc, s83, v99
	s_and_b64 vcc, s[10:11], vcc
	v_add_u32_e32 v99, 0xffffffa0, v0
	v_cndmask_b32_e32 v80, v80, v241, vcc
	v_cmp_gt_u32_e32 vcc, s83, v99
	s_and_b64 vcc, s[10:11], vcc
	v_add_u32_e32 v99, 0xffffffa1, v0
	v_cndmask_b32_e32 v81, v81, v241, vcc
	v_cmp_gt_u32_e32 vcc, s83, v99
	s_and_b64 vcc, s[10:11], vcc
	v_add_u32_e32 v99, 0xffffffa2, v0
	v_cndmask_b32_e32 v82, v82, v241, vcc
	v_cmp_gt_u32_e32 vcc, s83, v99
	s_and_b64 vcc, s[10:11], vcc
	v_add_u32_e32 v99, 0xffffffa7, v0
	v_cndmask_b32_e32 v83, v83, v241, vcc
	v_cmp_gt_u32_e32 vcc, s83, v99
	s_and_b64 vcc, s[10:11], vcc
	v_add_u32_e32 v99, 0xffffffa8, v0
	v_cndmask_b32_e32 v84, v84, v241, vcc
	v_cmp_gt_u32_e32 vcc, s83, v99
	s_and_b64 vcc, s[10:11], vcc
	v_add_u32_e32 v99, 0xffffffa9, v0
	v_cndmask_b32_e32 v85, v85, v241, vcc
	v_cmp_gt_u32_e32 vcc, s83, v99
; #define LAS __attribute__((address_space(3)))
; __device__ __forceinline__ void phase_attn(const Frame& F, int l, bool last, int ai, int na) {
;     ...
;             float mx = -1e30f;
; #pragma unroll
;             for (int kt = 0; kt < 2; ++kt)
; #pragma unroll
;                 for (int e = 0; e < 16; ++e) {
;                     if (win) { const int kp = kpos0 + kt * 32 + (e & 3) + 8 * (e >> 2) + 4 * hh; const int dd = kp - qpos; if (dd > 128 || dd < -128) sacc[kt][e] = -1e30f; }
;                     mx = fmaxf(mx, sacc[kt][e]); }
;             mx = fmaxf(mx, __shfl_xor(mx, 32));
;             const bool upd = mx > mrun + 8.0f;
;             const bool anyupd = __builtin_amdgcn_ballot_w64(upd) != 0ull;
;             const float mnew = upd ? mx : mrun;
;             float rs = 0.f;
; #pragma unroll
;             for (int kt = 0; kt < 2; ++kt)
; #pragma unroll
;                 for (int g4 = 0; g4 < 4; ++g4) { float pv4[4];
; #pragma unroll
;                     for (int e = 0; e < 4; ++e) { pv4[e] = __builtin_amdgcn_exp2f(sacc[kt][g4 * 4 + e] - mnew); rs += pv4[e]; }
;                     *(LAS u32x2*)(Pw + (r32 * 72 + kt * 32 + g4 * 8 + hh * 4) * 2) = (u32x2){pk_f16(pv4[0], pv4[1]), pk_f16(pv4[2], pv4[3])}; }
;             rs += __shfl_xor(rs, 32);
	s_and_b64 vcc, s[10:11], vcc
	v_add_u32_e32 v99, 0xffffffaa, v0
	v_cndmask_b32_e32 v86, v86, v241, vcc
	v_cmp_gt_u32_e32 vcc, s83, v99
	s_and_b64 vcc, s[10:11], vcc
	v_add_u32_e32 v99, 0xffffffaf, v0
	v_cndmask_b32_e32 v87, v87, v241, vcc
	v_cmp_gt_u32_e32 vcc, s83, v99
	s_and_b64 vcc, s[10:11], vcc
	v_add_u32_e32 v99, 0xffffffb0, v0
	v_cndmask_b32_e32 v88, v88, v241, vcc
	v_cmp_gt_u32_e32 vcc, s83, v99
	s_and_b64 vcc, s[10:11], vcc
	v_add_u32_e32 v99, 0xffffffb1, v0
	v_cndmask_b32_e32 v89, v89, v241, vcc
	v_cmp_gt_u32_e32 vcc, s83, v99
	s_and_b64 vcc, s[10:11], vcc
	v_add_u32_e32 v99, 0xffffffb2, v0
	v_cndmask_b32_e32 v90, v90, v241, vcc
	v_cmp_gt_u32_e32 vcc, s83, v99
	v_max3_f32 v4, v4, v13, v14
	s_and_b64 vcc, s[10:11], vcc
	v_add_u32_e32 v99, 0xffffffb7, v0
	v_max3_f32 v4, v4, v15, v96
	v_cndmask_b32_e32 v91, v91, v241, vcc
	v_cmp_gt_u32_e32 vcc, s83, v99
	v_max3_f32 v4, v4, v97, v98
	s_and_b64 vcc, s[10:11], vcc
	v_add_u32_e32 v99, 0xffffffb8, v0
	v_max3_f32 v4, v4, v80, v81
	v_cndmask_b32_e32 v92, v92, v241, vcc
	v_cmp_gt_u32_e32 vcc, s83, v99
	v_max3_f32 v4, v4, v82, v83
	s_and_b64 vcc, s[10:11], vcc
	v_add_u32_e32 v99, 0xffffffb9, v0
	v_max3_f32 v4, v4, v84, v85
	v_cndmask_b32_e32 v93, v93, v241, vcc
	v_cmp_gt_u32_e32 vcc, s83, v99
	v_max3_f32 v4, v4, v86, v87
	s_and_b64 vcc, s[10:11], vcc
	v_add_u32_e32 v0, 0xffffffba, v0
	v_max3_f32 v4, v4, v88, v89
	v_cndmask_b32_e32 v94, v94, v241, vcc
	v_cmp_gt_u32_e32 vcc, s83, v0
	v_max3_f32 v4, v4, v90, v91
	s_and_b64 vcc, s[10:11], vcc
	v_max3_f32 v4, v4, v92, v93
	v_cndmask_b32_e32 v95, v95, v241, vcc
	v_and_b32_e32 v99, 64, v237
	v_max3_f32 v0, v4, v94, v95
	v_xor_b32_e32 v4, 32, v237
	v_add_u32_e32 v99, 64, v99
	v_cmp_lt_i32_e32 vcc, v4, v99
	s_nop 1
	v_cndmask_b32_e32 v4, v237, v4, vcc
	v_lshlrev_b32_e32 v99, 2, v4
	ds_bpermute_b32 v4, v99, v0
	s_waitcnt lgkmcnt(0)
	v_max_f32_e32 v4, v4, v4
	v_max_f32_e32 v0, v0, v4
	v_add_f32_e32 v4, 0x41000000, v230
	v_cmp_gt_f32_e32 vcc, v0, v4
	s_nop 1
	v_cndmask_b32_e32 v0, v230, v0, vcc
	v_sub_f32_e32 v2, v2, v0
	v_exp_f32_e32 v2, v2
	v_sub_f32_e32 v3, v3, v0
	v_exp_f32_e32 v3, v3
	v_sub_f32_e32 v5, v5, v0
	v_sub_f32_e32 v6, v6, v0
	v_exp_f32_e32 v5, v5
	v_exp_f32_e32 v6, v6
	v_add_f32_e32 v4, 0, v2
	v_add_f32_e32 v4, v3, v4
	v_add_f32_e32 v4, v5, v4
	v_cvt_pk_f16_f32 v2, v2, v3
	v_cvt_pk_f16_f32 v3, v5, v6
	v_sub_f32_e32 v5, v7, v0
	v_add_f32_e32 v4, v6, v4
	v_exp_f32_e32 v5, v5
	v_sub_f32_e32 v6, v8, v0
	v_exp_f32_e32 v6, v6
	v_sub_f32_e32 v7, v9, v0
	v_exp_f32_e32 v7, v7
	v_sub_f32_e32 v8, v10, v0
	v_exp_f32_e32 v8, v8
	v_add_f32_e32 v4, v5, v4
	v_add_f32_e32 v4, v6, v4
	v_add_f32_e32 v4, v7, v4
	v_add_f32_e32 v9, v8, v4
	v_cvt_pk_f16_f32 v4, v5, v6
	v_cvt_pk_f16_f32 v5, v7, v8
	ds_write2_b64 v228, v[2:3], v[4:5] offset1:2
	v_sub_f32_e32 v2, v11, v0
	v_exp_f32_e32 v2, v2
	v_sub_f32_e32 v4, v12, v0
	v_exp_f32_e32 v4, v4
	v_sub_f32_e32 v5, v13, v0
	v_add_f32_e32 v3, v2, v9
	v_exp_f32_e32 v5, v5
	v_sub_f32_e32 v6, v14, v0
	v_add_f32_e32 v3, v4, v3
	v_exp_f32_e32 v6, v6
	v_cvt_pk_f16_f32 v2, v2, v4
	v_sub_f32_e32 v4, v15, v0
	v_exp_f32_e32 v4, v4
	v_add_f32_e32 v3, v5, v3
	v_add_f32_e32 v7, v6, v3
	v_cvt_pk_f16_f32 v3, v5, v6
	v_sub_f32_e32 v6, v96, v0
	v_add_f32_e32 v5, v4, v7
	v_exp_f32_e32 v6, v6
	v_sub_f32_e32 v7, v97, v0
	v_exp_f32_e32 v7, v7
	v_sub_f32_e32 v8, v98, v0
	v_exp_f32_e32 v8, v8
	v_add_f32_e32 v5, v6, v5
	v_add_f32_e32 v5, v7, v5
	v_cvt_pk_f16_f32 v4, v4, v6
	v_add_f32_e32 v9, v8, v5
	v_cvt_pk_f16_f32 v5, v7, v8
	ds_write2_b64 v228, v[2:3], v[4:5] offset0:4 offset1:6
	v_sub_f32_e32 v2, v80, v0
	v_exp_f32_e32 v2, v2
	v_sub_f32_e32 v4, v81, v0
	v_exp_f32_e32 v4, v4
	v_sub_f32_e32 v5, v82, v0
	v_add_f32_e32 v3, v2, v9
	v_exp_f32_e32 v5, v5
	v_sub_f32_e32 v6, v83, v0
	v_add_f32_e32 v3, v4, v3
	v_exp_f32_e32 v6, v6
	v_cvt_pk_f16_f32 v2, v2, v4
	v_sub_f32_e32 v4, v84, v0
	v_exp_f32_e32 v4, v4
	v_add_f32_e32 v3, v5, v3
	v_add_f32_e32 v7, v6, v3
	v_cvt_pk_f16_f32 v3, v5, v6
	v_sub_f32_e32 v6, v85, v0
	v_add_f32_e32 v5, v4, v7
	v_exp_f32_e32 v6, v6
	v_sub_f32_e32 v7, v86, v0
	v_exp_f32_e32 v7, v7
	v_sub_f32_e32 v8, v87, v0
	v_exp_f32_e32 v8, v8
	v_add_f32_e32 v5, v6, v5
	v_add_f32_e32 v5, v7, v5
	v_cvt_pk_f16_f32 v4, v4, v6
	v_add_f32_e32 v9, v8, v5
	v_cvt_pk_f16_f32 v5, v7, v8
	ds_write2_b64 v228, v[2:3], v[4:5] offset0:8 offset1:10
	v_sub_f32_e32 v2, v88, v0
	v_exp_f32_e32 v2, v2
	v_sub_f32_e32 v4, v89, v0
	v_exp_f32_e32 v4, v4
	v_sub_f32_e32 v5, v90, v0
	v_exp_f32_e32 v5, v5
	v_sub_f32_e32 v6, v91, v0
	v_exp_f32_e32 v6, v6
	v_add_f32_e32 v3, v2, v9
	v_add_f32_e32 v3, v4, v3
	v_add_f32_e32 v3, v5, v3
	v_cvt_pk_f16_f32 v4, v2, v4
	v_sub_f32_e32 v2, v92, v0
	v_add_f32_e32 v3, v6, v3
	v_cvt_pk_f16_f32 v5, v5, v6
	v_exp_f32_e32 v6, v2
	v_sub_f32_e32 v7, v94, v0
	v_exp_f32_e32 v7, v7
	v_sub_f32_e32 v8, v95, v0
	v_add_f32_e32 v2, v6, v3
	v_sub_f32_e32 v3, v93, v0
	v_exp_f32_e32 v3, v3
	v_exp_f32_e32 v8, v8
	v_add_f32_e32 v2, v3, v2
	v_add_f32_e32 v2, v7, v2
	v_add_f32_e32 v2, v8, v2
	v_cvt_pk_f16_f32 v6, v6, v3
	ds_bpermute_b32 v3, v99, v2
	v_cvt_pk_f16_f32 v7, v7, v8
	ds_write2_b64 v228, v[4:5], v[6:7] offset0:12 offset1:14
	s_cbranch_vccz .LBB0_617
; __device__ __forceinline__ void phase_attn(const Frame& F, int l, bool last, int ai, int na) {
;     ...
;             if (anyupd) { const float alpha = __builtin_amdgcn_exp2f(mrun - mnew); lrun *= alpha;
; #pragma unroll
;                 for (int dt = 0; dt < 4; ++dt)
; #pragma unroll
;                     for (int e = 0; e < 16; ++e) oacc[dt][e] *= alpha; }
.Lattn_rescale:
	v_sub_f32_e32 v4, v230, v0
	v_exp_f32_e32 v4, v4
	s_nop 0
	v_pk_mul_f32 v[78:79], v[78:79], v[4:5] op_sel_hi:[1,0]
	v_pk_mul_f32 v[76:77], v[76:77], v[4:5] op_sel_hi:[1,0]
	v_pk_mul_f32 v[74:75], v[74:75], v[4:5] op_sel_hi:[1,0]
	v_pk_mul_f32 v[72:73], v[72:73], v[4:5] op_sel_hi:[1,0]
	v_pk_mul_f32 v[70:71], v[70:71], v[4:5] op_sel_hi:[1,0]
	v_pk_mul_f32 v[68:69], v[68:69], v[4:5] op_sel_hi:[1,0]
	v_pk_mul_f32 v[66:67], v[66:67], v[4:5] op_sel_hi:[1,0]
	v_pk_mul_f32 v[64:65], v[64:65], v[4:5] op_sel_hi:[1,0]
	v_pk_mul_f32 v[62:63], v[62:63], v[4:5] op_sel_hi:[1,0]
	v_pk_mul_f32 v[60:61], v[60:61], v[4:5] op_sel_hi:[1,0]
	v_pk_mul_f32 v[58:59], v[58:59], v[4:5] op_sel_hi:[1,0]
	v_pk_mul_f32 v[56:57], v[56:57], v[4:5] op_sel_hi:[1,0]
	v_pk_mul_f32 v[54:55], v[54:55], v[4:5] op_sel_hi:[1,0]
	v_pk_mul_f32 v[52:53], v[52:53], v[4:5] op_sel_hi:[1,0]
	v_pk_mul_f32 v[50:51], v[50:51], v[4:5] op_sel_hi:[1,0]
	v_pk_mul_f32 v[48:49], v[48:49], v[4:5] op_sel_hi:[1,0]
	v_pk_mul_f32 v[46:47], v[46:47], v[4:5] op_sel_hi:[1,0]
	v_pk_mul_f32 v[44:45], v[44:45], v[4:5] op_sel_hi:[1,0]
	v_pk_mul_f32 v[42:43], v[42:43], v[4:5] op_sel_hi:[1,0]
	v_pk_mul_f32 v[40:41], v[40:41], v[4:5] op_sel_hi:[1,0]
	v_pk_mul_f32 v[38:39], v[38:39], v[4:5] op_sel_hi:[1,0]
	v_pk_mul_f32 v[36:37], v[36:37], v[4:5] op_sel_hi:[1,0]
	v_pk_mul_f32 v[34:35], v[34:35], v[4:5] op_sel_hi:[1,0]
	v_pk_mul_f32 v[32:33], v[32:33], v[4:5] op_sel_hi:[1,0]
	v_pk_mul_f32 v[30:31], v[30:31], v[4:5] op_sel_hi:[1,0]
	v_pk_mul_f32 v[28:29], v[28:29], v[4:5] op_sel_hi:[1,0]
	v_pk_mul_f32 v[26:27], v[26:27], v[4:5] op_sel_hi:[1,0]
	v_pk_mul_f32 v[24:25], v[24:25], v[4:5] op_sel_hi:[1,0]
	v_pk_mul_f32 v[22:23], v[22:23], v[4:5] op_sel_hi:[1,0]
	v_pk_mul_f32 v[20:21], v[20:21], v[4:5] op_sel_hi:[1,0]
	v_pk_mul_f32 v[18:19], v[18:19], v[4:5] op_sel_hi:[1,0]
	v_pk_mul_f32 v[16:17], v[16:17], v[4:5] op_sel_hi:[1,0]
	v_mul_f32_e32 v171, v171, v4

; #define LAS __attribute__((address_space(3)))
; __device__ __forceinline__ void phase_attn(const Frame& F, int l, bool last, int ai, int na) {
;     ...
;             float mx = -1e30f;
; #pragma unroll
;             for (int kt = 0; kt < 2; ++kt)
; #pragma unroll
;                 for (int e = 0; e < 16; ++e) {
;                     if (win) { const int kp = kpos0 + kt * 32 + (e & 3) + 8 * (e >> 2) + 4 * hh; const int dd = kp - qpos; if (dd > 128 || dd < -128) sacc[kt][e] = -1e30f; }
;                     mx = fmaxf(mx, sacc[kt][e]); }
;             mx = fmaxf(mx, __shfl_xor(mx, 32));
;             const bool upd = mx > mrun + 8.0f;
;             const bool anyupd = __builtin_amdgcn_ballot_w64(upd) != 0ull;
;             const float mnew = upd ? mx : mrun;
;             float rs = 0.f;
; #pragma unroll
;             for (int kt = 0; kt < 2; ++kt)
; #pragma unroll
;                 for (int g4 = 0; g4 < 4; ++g4) { float pv4[4];
; #pragma unroll
;                     for (int e = 0; e < 4; ++e) { pv4[e] = __builtin_amdgcn_exp2f(sacc[kt][g4 * 4 + e] - mnew); rs += pv4[e]; }
;                     *(LAS u32x2*)(Pw + (r32 * 72 + kt * 32 + g4 * 8 + hh * 4) * 2) = (u32x2){pk_f16(pv4[0], pv4[1]), pk_f16(pv4[2], pv4[3])}; }
;             rs += __shfl_xor(rs, 32);
;             if (anyupd) { const float alpha = __builtin_amdgcn_exp2f(mrun - mnew); lrun *= alpha;
; #pragma unroll
;                 for (int dt = 0; dt < 4; ++dt)
; #pragma unroll
;                     for (int e = 0; e < 16; ++e) oacc[dt][e] *= alpha; }
;             lrun += rs; mrun = mnew;
.Lattn_nomask:
	s_nop 8
	v_max3_f32 v4, v96, s3, v97
	v_max3_f32 v4, v4, v98, v99
	v_max3_f32 v4, v4, v100, v101
	v_max3_f32 v4, v4, v102, v103
	v_max3_f32 v4, v4, v104, v105
	v_max3_f32 v4, v4, v106, v107
	v_max3_f32 v4, v4, v108, v109
	v_max3_f32 v4, v4, v110, v111
	v_max3_f32 v4, v4, v80, v81
	v_max3_f32 v4, v4, v82, v83
	v_max3_f32 v4, v4, v84, v85
	v_max3_f32 v4, v4, v86, v87
	v_max3_f32 v4, v4, v88, v89
	v_max3_f32 v4, v4, v90, v91
	v_max3_f32 v4, v4, v92, v93
	v_and_b32_e32 v231, 64, v237
	v_max3_f32 v0, v4, v94, v95
	v_xor_b32_e32 v4, 32, v237
	v_add_u32_e32 v231, 64, v231
	v_cmp_lt_i32_e32 vcc, v4, v231
	s_nop 1
	v_cndmask_b32_e32 v4, v237, v4, vcc
	v_lshlrev_b32_e32 v231, 2, v4
	ds_bpermute_b32 v4, v231, v0
	s_waitcnt lgkmcnt(0)
	v_max_f32_e32 v4, v4, v4
	v_max_f32_e32 v0, v0, v4
	v_add_f32_e32 v4, 0x41000000, v230
	v_cmp_gt_f32_e32 vcc, v0, v4
	s_nop 1
	v_cndmask_b32_e32 v0, v230, v0, vcc
	v_sub_f32_e32 v2, v96, v0
	v_exp_f32_e32 v2, v2
	v_sub_f32_e32 v3, v97, v0
	v_exp_f32_e32 v3, v3
	v_sub_f32_e32 v5, v98, v0
	v_sub_f32_e32 v6, v99, v0
	v_exp_f32_e32 v5, v5
	v_exp_f32_e32 v6, v6
	v_add_f32_e32 v4, 0, v2
	v_add_f32_e32 v4, v3, v4
	v_add_f32_e32 v4, v5, v4
	v_cvt_pk_f16_f32 v2, v2, v3
	v_cvt_pk_f16_f32 v3, v5, v6
	v_sub_f32_e32 v5, v100, v0
	v_add_f32_e32 v4, v6, v4
	v_exp_f32_e32 v5, v5
	v_sub_f32_e32 v6, v101, v0
	v_exp_f32_e32 v6, v6
	v_sub_f32_e32 v7, v102, v0
	v_exp_f32_e32 v7, v7
	v_sub_f32_e32 v8, v103, v0
	v_exp_f32_e32 v8, v8
	v_add_f32_e32 v4, v5, v4
	v_add_f32_e32 v4, v6, v4
	v_add_f32_e32 v4, v7, v4
	v_add_f32_e32 v9, v8, v4
	v_cvt_pk_f16_f32 v4, v5, v6
	v_cvt_pk_f16_f32 v5, v7, v8
	ds_write2_b64 v228, v[2:3], v[4:5] offset1:2
	v_sub_f32_e32 v2, v104, v0
	v_exp_f32_e32 v2, v2
	v_sub_f32_e32 v4, v105, v0
	v_exp_f32_e32 v4, v4
	v_sub_f32_e32 v5, v106, v0
	v_add_f32_e32 v3, v2, v9
	v_exp_f32_e32 v5, v5
	v_sub_f32_e32 v6, v107, v0
	v_add_f32_e32 v3, v4, v3
	v_exp_f32_e32 v6, v6
	v_cvt_pk_f16_f32 v2, v2, v4
	v_sub_f32_e32 v4, v108, v0
	v_exp_f32_e32 v4, v4
	v_add_f32_e32 v3, v5, v3
	v_add_f32_e32 v7, v6, v3
	v_cvt_pk_f16_f32 v3, v5, v6
	v_sub_f32_e32 v6, v109, v0
	v_add_f32_e32 v5, v4, v7
	v_exp_f32_e32 v6, v6
	v_sub_f32_e32 v7, v110, v0
	v_exp_f32_e32 v7, v7
	v_sub_f32_e32 v8, v111, v0
	v_exp_f32_e32 v8, v8
	v_add_f32_e32 v5, v6, v5
	v_add_f32_e32 v5, v7, v5
	v_cvt_pk_f16_f32 v4, v4, v6
	v_add_f32_e32 v9, v8, v5
	v_cvt_pk_f16_f32 v5, v7, v8
	ds_write2_b64 v228, v[2:3], v[4:5] offset0:4 offset1:6
	v_sub_f32_e32 v2, v80, v0
	v_exp_f32_e32 v2, v2
	v_sub_f32_e32 v4, v81, v0
	v_exp_f32_e32 v4, v4
	v_sub_f32_e32 v5, v82, v0
	v_add_f32_e32 v3, v2, v9
	v_exp_f32_e32 v5, v5
	v_sub_f32_e32 v6, v83, v0
	v_add_f32_e32 v3, v4, v3
	v_exp_f32_e32 v6, v6
	v_cvt_pk_f16_f32 v2, v2, v4
	v_sub_f32_e32 v4, v84, v0
	v_exp_f32_e32 v4, v4
	v_add_f32_e32 v3, v5, v3
	v_add_f32_e32 v7, v6, v3
	v_cvt_pk_f16_f32 v3, v5, v6
	v_sub_f32_e32 v6, v85, v0
	v_add_f32_e32 v5, v4, v7
	v_exp_f32_e32 v6, v6
	v_sub_f32_e32 v7, v86, v0
	v_exp_f32_e32 v7, v7
	v_sub_f32_e32 v8, v87, v0
	v_exp_f32_e32 v8, v8
	v_add_f32_e32 v5, v6, v5
	v_add_f32_e32 v5, v7, v5
	v_cvt_pk_f16_f32 v4, v4, v6
	v_add_f32_e32 v9, v8, v5
	v_cvt_pk_f16_f32 v5, v7, v8
	ds_write2_b64 v228, v[2:3], v[4:5] offset0:8 offset1:10
	v_sub_f32_e32 v2, v88, v0
	v_exp_f32_e32 v2, v2
	v_sub_f32_e32 v4, v89, v0
	v_exp_f32_e32 v4, v4
	v_sub_f32_e32 v5, v90, v0
	v_exp_f32_e32 v5, v5
	v_sub_f32_e32 v6, v91, v0
	v_exp_f32_e32 v6, v6
	v_add_f32_e32 v3, v2, v9
	v_add_f32_e32 v3, v4, v3
	v_add_f32_e32 v3, v5, v3
	v_cvt_pk_f16_f32 v4, v2, v4
	v_sub_f32_e32 v2, v92, v0
	v_add_f32_e32 v3, v6, v3
	v_cvt_pk_f16_f32 v5, v5, v6
	v_exp_f32_e32 v6, v2
	v_sub_f32_e32 v7, v94, v0
	v_exp_f32_e32 v7, v7
	v_sub_f32_e32 v8, v95, v0
	v_add_f32_e32 v2, v6, v3
	v_sub_f32_e32 v3, v93, v0
	v_exp_f32_e32 v3, v3
	v_exp_f32_e32 v8, v8
	v_add_f32_e32 v2, v3, v2
	v_add_f32_e32 v2, v7, v2
	v_add_f32_e32 v2, v8, v2
	v_cvt_pk_f16_f32 v6, v6, v3
	ds_bpermute_b32 v3, v231, v2
	v_cvt_pk_f16_f32 v7, v7, v8
	ds_write2_b64 v228, v[4:5], v[6:7] offset0:12 offset1:14
	s_cbranch_vccz .LBB0_617
	s_branch .Lattn_rescale
